# v15 + P1 SwiGLU epilogue: 8 rs row-scale loads prefetched at top, per-group vmcnt(0) round trips removed
# speedup vs baseline: 1.0018x; 1.0018x over previous
.LBB0_425:
	v_mov_b32_e32 v148, v151
	v_cndmask_b32_e64 v149, 0, 1, s[10:11]
	v_and_or_b32 v146, v148, 15, s42
	v_lshl_add_u32 v146, s8, 8, v146
	v_ashrrev_i32_e32 v147, 31, v146
	v_mov_b32_e32 v150, 1.0
	v_cmp_ne_u32_e64 s[8:9], 1, v149
	s_andn2_b64 vcc, exec, s[10:11]
	v_mov_b32_e32 v152, 1.0
	s_cbranch_vccnz .LBB0_427
	v_readlane_b32 s28, v245, 16
	v_readlane_b32 s29, v245, 17
	s_nop 1
	v_lshl_add_u64 v[158:159], v[146:147], 2, s[28:29]
	global_load_dword v152, v[158:159], off
	global_load_dword v187, v[158:159], off offset:64
	global_load_dword v188, v[158:159], off offset:128
	global_load_dword v189, v[158:159], off offset:192
	global_load_dword v190, v[158:159], off offset:512
	global_load_dword v191, v[158:159], off offset:576
	global_load_dword v192, v[158:159], off offset:640
	global_load_dword v193, v[158:159], off offset:704
.LBB0_427:
	s_waitcnt vmcnt(0)
	v_pk_mul_f32 v[126:127], v[126:127], v[152:153] op_sel_hi:[1,0]
	v_lshlrev_b64 v[158:159], 7, v[146:147]
	v_mul_f32_e32 v147, 0xbfb8aa3b, v126
	v_exp_f32_e32 v147, v147
	v_mul_f32_e32 v157, 0xbfb8aa3b, v127
	v_exp_f32_e32 v157, v157
	v_pk_mul_f32 v[160:161], v[116:117], v[152:153] op_sel_hi:[1,0]
	v_add_f32_e32 v116, 1.0, v147
	v_rcp_f32_e32 v147, v116
	v_add_f32_e32 v116, 1.0, v157
	v_pk_mul_f32 v[128:129], v[128:129], v[152:153] op_sel_hi:[1,0]
	v_pk_mul_f32 v[118:119], v[118:119], v[152:153] op_sel_hi:[1,0]
	v_rcp_f32_e32 v157, v116
	v_pk_mul_f32 v[116:117], v[114:115], v[152:153] op_sel_hi:[1,0]
	v_mul_f32_e32 v114, v126, v147
	v_mul_f32_e32 v114, v118, v114
	v_mul_f32_e32 v118, 0xbfb8aa3b, v128
	v_mul_f32_e32 v126, 0xbfb8aa3b, v129
	v_exp_f32_e32 v118, v118
	v_exp_f32_e32 v126, v126
	v_mul_f32_e32 v115, v127, v157
	v_mul_f32_e32 v115, v119, v115
	v_add_f32_e32 v118, 1.0, v118
	v_add_f32_e32 v119, 1.0, v126
	v_rcp_f32_e32 v118, v118
	v_rcp_f32_e32 v119, v119
	v_pk_mul_f32 v[122:123], v[122:123], v[152:153] op_sel_hi:[1,0]
	v_pk_mul_f32 v[120:121], v[120:121], v[152:153] op_sel_hi:[1,0]
	v_cvt_pk_bf16_f32 v114, v114, v115
	v_mul_f32_e32 v115, v128, v118
	v_mul_f32_e32 v118, v129, v119
	v_mul_f32_e32 v119, 0xbfb8aa3b, v122
	v_mul_f32_e32 v115, v120, v115
	v_exp_f32_e32 v119, v119
	v_mul_f32_e32 v120, 0xbfb8aa3b, v123
	v_exp_f32_e32 v120, v120
	v_pk_mul_f32 v[124:125], v[124:125], v[152:153] op_sel_hi:[1,0]
	v_add_f32_e32 v119, 1.0, v119
	v_rcp_f32_e32 v119, v119
	v_add_f32_e32 v120, 1.0, v120
	v_rcp_f32_e32 v120, v120
	v_mul_f32_e32 v118, v121, v118
	v_cvt_pk_bf16_f32 v115, v115, v118
	v_mul_f32_e32 v118, v122, v119
	v_mul_f32_e32 v119, 0xbfb8aa3b, v124
	v_mul_f32_e32 v116, v116, v118
	v_mul_f32_e32 v118, v123, v120
	v_exp_f32_e32 v119, v119
	v_mul_f32_e32 v120, 0xbfb8aa3b, v125
	v_exp_f32_e32 v120, v120
	s_lshl_b32 s19, s26, 7
	s_or_b32 s19, s19, s43
	s_ashr_i32 s28, s19, 6
	v_mul_f32_e32 v117, v117, v118
	v_add_f32_e32 v118, 1.0, v119
	v_lshrrev_b32_e32 v148, 1, v148
	s_ashr_i32 s29, s28, 31
	v_rcp_f32_e32 v118, v118
	v_add_f32_e32 v119, 1.0, v120
	s_lshl_b64 s[28:29], s[28:29], 19
	v_and_or_b32 v148, v148, 24, s46
	v_rcp_f32_e32 v119, v119
	v_or_b32_e32 v148, s28, v148
	v_mov_b32_e32 v149, s29
	v_readlane_b32 s28, v245, 14
	v_readlane_b32 s29, v245, 15
	v_cvt_pk_bf16_f32 v116, v116, v117
	v_mul_f32_e32 v117, v124, v118
	v_mul_f32_e32 v117, v160, v117
	v_lshl_add_u64 v[158:159], s[28:29], 0, v[158:159]
	v_lshl_add_u64 v[158:159], v[148:149], 1, v[158:159]
	v_mul_f32_e32 v118, v125, v119
	v_mul_f32_e32 v118, v161, v118
	v_cvt_pk_bf16_f32 v117, v117, v118
	global_store_dwordx4 v[158:159], v[114:117], off
	s_and_b64 vcc, exec, s[8:9]
	s_nop 0
	v_or_b32_e32 v114, 16, v146
	v_ashrrev_i32_e32 v115, 31, v114
	s_cbranch_vccnz .LBB0_429
	v_readlane_b32 s28, v245, 16
	v_readlane_b32 s29, v245, 17
	s_nop 1
	v_lshl_add_u64 v[116:117], v[114:115], 2, s[28:29]
	v_mov_b32_e32 v150, v187
.LBB0_429:
	v_pk_mul_f32 v[110:111], v[110:111], v[150:151] op_sel_hi:[1,0]
	v_pk_mul_f32 v[116:117], v[100:101], v[150:151] op_sel_hi:[1,0]
	v_mul_f32_e32 v100, 0xbfb8aa3b, v110
	v_exp_f32_e32 v100, v100
	v_pk_mul_f32 v[118:119], v[98:99], v[150:151] op_sel_hi:[1,0]
	v_mul_f32_e32 v101, 0xbfb8aa3b, v111
	v_exp_f32_e32 v101, v101
	v_add_f32_e32 v98, 1.0, v100
	v_rcp_f32_e32 v99, v98
	v_pk_mul_f32 v[112:113], v[112:113], v[150:151] op_sel_hi:[1,0]
	v_pk_mul_f32 v[102:103], v[102:103], v[150:151] op_sel_hi:[1,0]
	v_add_f32_e32 v98, 1.0, v101
	v_mul_f32_e32 v99, v110, v99
	v_mul_f32_e32 v99, v102, v99
	v_mul_f32_e32 v101, 0xbfb8aa3b, v112
	v_mul_f32_e32 v102, 0xbfb8aa3b, v113
	v_exp_f32_e32 v101, v101
	v_exp_f32_e32 v102, v102
	v_rcp_f32_e32 v100, v98
	v_pk_mul_f32 v[106:107], v[106:107], v[150:151] op_sel_hi:[1,0]
	v_add_f32_e32 v101, 1.0, v101
	v_add_f32_e32 v102, 1.0, v102
	v_rcp_f32_e32 v101, v101
	v_rcp_f32_e32 v102, v102
	v_mul_f32_e32 v100, v111, v100
	v_mul_f32_e32 v100, v103, v100
	v_cvt_pk_bf16_f32 v100, v99, v100
	v_mul_f32_e32 v99, v112, v101
	v_mul_f32_e32 v101, v113, v102
	v_mul_f32_e32 v102, 0xbfb8aa3b, v106
	v_mul_f32_e32 v103, 0xbfb8aa3b, v107
	v_exp_f32_e32 v102, v102
	v_exp_f32_e32 v103, v103
	v_pk_mul_f32 v[104:105], v[104:105], v[150:151] op_sel_hi:[1,0]
	v_pk_mul_f32 v[108:109], v[108:109], v[150:151] op_sel_hi:[1,0]
	v_add_f32_e32 v102, 1.0, v102
	v_add_f32_e32 v103, 1.0, v103
	v_rcp_f32_e32 v102, v102
	v_rcp_f32_e32 v103, v103
	v_mul_f32_e32 v99, v104, v99
	v_mul_f32_e32 v101, v105, v101
	v_cvt_pk_bf16_f32 v101, v99, v101
	v_mul_f32_e32 v99, v106, v102
	v_mul_f32_e32 v102, v107, v103
	v_mul_f32_e32 v103, 0xbfb8aa3b, v108
	v_mul_f32_e32 v104, 0xbfb8aa3b, v109
	v_exp_f32_e32 v103, v103
	v_exp_f32_e32 v104, v104
	v_readlane_b32 s28, v245, 14
	v_lshlrev_b64 v[114:115], 7, v[114:115]
	v_add_f32_e32 v103, 1.0, v103
	v_add_f32_e32 v104, 1.0, v104
	v_rcp_f32_e32 v103, v103
	v_rcp_f32_e32 v104, v104
	v_readlane_b32 s29, v245, 15
	v_mul_f32_e32 v99, v118, v99
	v_mul_f32_e32 v102, v119, v102
	v_lshl_add_u64 v[114:115], s[28:29], 0, v[114:115]
	v_cvt_pk_bf16_f32 v102, v99, v102
	v_mul_f32_e32 v99, v108, v103
	v_mul_f32_e32 v103, v109, v104
	v_lshl_add_u64 v[114:115], v[148:149], 1, v[114:115]
	v_mul_f32_e32 v103, v117, v103
	v_mul_f32_e32 v99, v116, v99
	v_cvt_pk_bf16_f32 v103, v99, v103
	global_store_dwordx4 v[114:115], v[100:103], off
	v_mov_b32_e32 v98, 1.0
	s_and_b64 vcc, exec, s[8:9]
	v_or_b32_e32 v102, 32, v146
	v_ashrrev_i32_e32 v103, 31, v102
	v_mov_b32_e32 v100, 1.0
	s_cbranch_vccnz .LBB0_431
	v_readlane_b32 s28, v245, 16
	v_readlane_b32 s29, v245, 17
	s_nop 1
	v_lshl_add_u64 v[100:101], v[102:103], 2, s[28:29]
	v_mov_b32_e32 v100, v188
.LBB0_431:
	v_pk_mul_f32 v[94:95], v[94:95], v[100:101] op_sel_hi:[1,0]
	v_pk_mul_f32 v[96:97], v[96:97], v[100:101] op_sel_hi:[1,0]
	v_pk_mul_f32 v[92:93], v[92:93], v[100:101] op_sel_hi:[1,0]
	v_pk_mul_f32 v[90:91], v[90:91], v[100:101] op_sel_hi:[1,0]
	v_pk_mul_f32 v[88:89], v[88:89], v[100:101] op_sel_hi:[1,0]
	v_pk_mul_f32 v[86:87], v[86:87], v[100:101] op_sel_hi:[1,0]
	v_mul_f32_e32 v99, 0xbfb8aa3b, v94
	v_mul_f32_e32 v101, 0xbfb8aa3b, v95
	v_exp_f32_e32 v99, v99
	v_exp_f32_e32 v101, v101
	v_readlane_b32 s28, v245, 14
	v_lshlrev_b64 v[102:103], 7, v[102:103]
	v_readlane_b32 s29, v245, 15
	v_pk_mul_f32 v[104:105], v[84:85], v[100:101] op_sel_hi:[1,0]
	v_add_f32_e32 v84, 1.0, v99
	v_rcp_f32_e32 v99, v84
	v_add_f32_e32 v84, 1.0, v101
	v_rcp_f32_e32 v101, v84
	v_lshl_add_u64 v[102:103], s[28:29], 0, v[102:103]
	v_lshl_add_u64 v[102:103], v[148:149], 1, v[102:103]
	s_and_b64 vcc, exec, s[8:9]
	v_pk_mul_f32 v[84:85], v[82:83], v[100:101] op_sel_hi:[1,0]
	v_mul_f32_e32 v82, v94, v99
	v_mul_f32_e32 v82, v86, v82
	v_mul_f32_e32 v86, 0xbfb8aa3b, v96
	v_mul_f32_e32 v94, 0xbfb8aa3b, v97
	v_exp_f32_e32 v86, v86
	v_exp_f32_e32 v94, v94
	v_mul_f32_e32 v83, v95, v101
	v_mul_f32_e32 v83, v87, v83
	v_add_f32_e32 v86, 1.0, v86
	v_add_f32_e32 v87, 1.0, v94
	v_rcp_f32_e32 v86, v86
	v_rcp_f32_e32 v87, v87
	v_cvt_pk_bf16_f32 v82, v82, v83
	v_mul_f32_e32 v83, v96, v86
	v_mul_f32_e32 v86, v97, v87
	v_mul_f32_e32 v87, 0xbfb8aa3b, v90
	v_mul_f32_e32 v83, v88, v83
	v_exp_f32_e32 v87, v87
	v_mul_f32_e32 v88, 0xbfb8aa3b, v91
	v_exp_f32_e32 v88, v88
	v_mul_f32_e32 v86, v89, v86
	v_add_f32_e32 v87, 1.0, v87
	v_rcp_f32_e32 v87, v87
	v_add_f32_e32 v88, 1.0, v88
	v_rcp_f32_e32 v88, v88
	v_cvt_pk_bf16_f32 v83, v83, v86
	v_mul_f32_e32 v86, v90, v87
	v_mul_f32_e32 v87, 0xbfb8aa3b, v92
	v_mul_f32_e32 v84, v84, v86
	v_mul_f32_e32 v86, v91, v88
	v_exp_f32_e32 v87, v87
	v_mul_f32_e32 v88, 0xbfb8aa3b, v93
	v_exp_f32_e32 v88, v88
	v_mul_f32_e32 v85, v85, v86
	v_add_f32_e32 v86, 1.0, v87
	v_rcp_f32_e32 v86, v86
	v_add_f32_e32 v87, 1.0, v88
	v_rcp_f32_e32 v87, v87
	v_cvt_pk_bf16_f32 v84, v84, v85
	v_mul_f32_e32 v85, v92, v86
	v_mul_f32_e32 v85, v104, v85
	v_mul_f32_e32 v86, v93, v87
	v_mul_f32_e32 v86, v105, v86
	v_cvt_pk_bf16_f32 v85, v85, v86
	global_store_dwordx4 v[102:103], v[82:85], off
	s_nop 1
	v_or_b32_e32 v82, 48, v146
	v_ashrrev_i32_e32 v83, 31, v82
	s_cbranch_vccnz .LBB0_433
	v_readlane_b32 s28, v245, 16
	v_readlane_b32 s29, v245, 17
	s_nop 1
	v_lshl_add_u64 v[84:85], v[82:83], 2, s[28:29]
	v_mov_b32_e32 v98, v189
.LBB0_433:
	v_pk_mul_f32 v[78:79], v[78:79], v[98:99] op_sel_hi:[1,0]
	v_pk_mul_f32 v[84:85], v[68:69], v[98:99] op_sel_hi:[1,0]
	v_mul_f32_e32 v68, 0xbfb8aa3b, v78
	v_exp_f32_e32 v68, v68
	v_pk_mul_f32 v[86:87], v[66:67], v[98:99] op_sel_hi:[1,0]
	v_mul_f32_e32 v69, 0xbfb8aa3b, v79
	v_exp_f32_e32 v69, v69
	v_add_f32_e32 v66, 1.0, v68
	v_rcp_f32_e32 v67, v66
	v_pk_mul_f32 v[80:81], v[80:81], v[98:99] op_sel_hi:[1,0]
	v_pk_mul_f32 v[70:71], v[70:71], v[98:99] op_sel_hi:[1,0]
	v_add_f32_e32 v66, 1.0, v69
	v_mul_f32_e32 v67, v78, v67
	v_mul_f32_e32 v67, v70, v67
	v_mul_f32_e32 v69, 0xbfb8aa3b, v80
	v_mul_f32_e32 v70, 0xbfb8aa3b, v81
	v_exp_f32_e32 v69, v69
	v_exp_f32_e32 v70, v70
	v_rcp_f32_e32 v68, v66
	v_pk_mul_f32 v[74:75], v[74:75], v[98:99] op_sel_hi:[1,0]
	v_add_f32_e32 v69, 1.0, v69
	v_add_f32_e32 v70, 1.0, v70
	v_rcp_f32_e32 v69, v69
	v_rcp_f32_e32 v70, v70
	v_mul_f32_e32 v68, v79, v68
	v_mul_f32_e32 v68, v71, v68
	v_cvt_pk_bf16_f32 v68, v67, v68
	v_mul_f32_e32 v67, v80, v69
	v_mul_f32_e32 v69, v81, v70
	v_mul_f32_e32 v70, 0xbfb8aa3b, v74
	v_mul_f32_e32 v71, 0xbfb8aa3b, v75
	v_exp_f32_e32 v70, v70
	v_exp_f32_e32 v71, v71
	v_pk_mul_f32 v[72:73], v[72:73], v[98:99] op_sel_hi:[1,0]
	v_pk_mul_f32 v[76:77], v[76:77], v[98:99] op_sel_hi:[1,0]
	v_add_f32_e32 v70, 1.0, v70
	v_add_f32_e32 v71, 1.0, v71
	v_rcp_f32_e32 v70, v70
	v_rcp_f32_e32 v71, v71
	v_mul_f32_e32 v67, v72, v67
	v_mul_f32_e32 v69, v73, v69
	v_cvt_pk_bf16_f32 v69, v67, v69
	v_mul_f32_e32 v67, v74, v70
	v_mul_f32_e32 v70, v75, v71
	v_mul_f32_e32 v71, 0xbfb8aa3b, v76
	v_mul_f32_e32 v72, 0xbfb8aa3b, v77
	v_exp_f32_e32 v71, v71
	v_exp_f32_e32 v72, v72
	v_readlane_b32 s28, v245, 14
	v_lshlrev_b64 v[82:83], 7, v[82:83]
	v_add_f32_e32 v71, 1.0, v71
	v_add_f32_e32 v72, 1.0, v72
	v_rcp_f32_e32 v71, v71
	v_rcp_f32_e32 v72, v72
	v_readlane_b32 s29, v245, 15
	v_mul_f32_e32 v67, v86, v67
	v_mul_f32_e32 v70, v87, v70
	v_lshl_add_u64 v[82:83], s[28:29], 0, v[82:83]
	v_cvt_pk_bf16_f32 v70, v67, v70
	v_mul_f32_e32 v67, v76, v71
	v_mul_f32_e32 v71, v77, v72
	v_lshl_add_u64 v[82:83], v[148:149], 1, v[82:83]
	v_mul_f32_e32 v71, v85, v71
	v_mul_f32_e32 v67, v84, v67
	v_cvt_pk_bf16_f32 v71, v67, v71
	global_store_dwordx4 v[82:83], v[68:71], off
	v_mov_b32_e32 v66, 1.0
	s_and_b64 vcc, exec, s[8:9]
	v_add_u32_e32 v70, 0x80, v146
	v_ashrrev_i32_e32 v71, 31, v70
	v_mov_b32_e32 v68, 1.0
	s_cbranch_vccnz .LBB0_435
	v_readlane_b32 s28, v245, 16
	v_readlane_b32 s29, v245, 17
	s_nop 1
	v_lshl_add_u64 v[68:69], v[70:71], 2, s[28:29]
	v_mov_b32_e32 v68, v190
.LBB0_435:
	v_pk_mul_f32 v[62:63], v[62:63], v[68:69] op_sel_hi:[1,0]
	v_pk_mul_f32 v[64:65], v[64:65], v[68:69] op_sel_hi:[1,0]
	v_pk_mul_f32 v[60:61], v[60:61], v[68:69] op_sel_hi:[1,0]
	v_pk_mul_f32 v[58:59], v[58:59], v[68:69] op_sel_hi:[1,0]
	v_pk_mul_f32 v[56:57], v[56:57], v[68:69] op_sel_hi:[1,0]
	v_pk_mul_f32 v[54:55], v[54:55], v[68:69] op_sel_hi:[1,0]
	v_mul_f32_e32 v67, 0xbfb8aa3b, v62
	v_mul_f32_e32 v69, 0xbfb8aa3b, v63
	v_exp_f32_e32 v67, v67
	v_exp_f32_e32 v69, v69
	v_readlane_b32 s28, v245, 14
	v_lshlrev_b64 v[70:71], 7, v[70:71]
	v_readlane_b32 s29, v245, 15
	v_pk_mul_f32 v[72:73], v[52:53], v[68:69] op_sel_hi:[1,0]
	v_add_f32_e32 v52, 1.0, v67
	v_rcp_f32_e32 v67, v52
	v_add_f32_e32 v52, 1.0, v69
	v_rcp_f32_e32 v69, v52
	v_lshl_add_u64 v[70:71], s[28:29], 0, v[70:71]
	v_lshl_add_u64 v[70:71], v[148:149], 1, v[70:71]
	s_and_b64 vcc, exec, s[8:9]
	v_pk_mul_f32 v[52:53], v[50:51], v[68:69] op_sel_hi:[1,0]
	v_mul_f32_e32 v50, v62, v67
	v_mul_f32_e32 v50, v54, v50
	v_mul_f32_e32 v54, 0xbfb8aa3b, v64
	v_mul_f32_e32 v62, 0xbfb8aa3b, v65
	v_exp_f32_e32 v54, v54
	v_exp_f32_e32 v62, v62
	v_mul_f32_e32 v51, v63, v69
	v_mul_f32_e32 v51, v55, v51
	v_add_f32_e32 v54, 1.0, v54
	v_add_f32_e32 v55, 1.0, v62
	v_rcp_f32_e32 v54, v54
	v_rcp_f32_e32 v55, v55
	v_cvt_pk_bf16_f32 v50, v50, v51
	v_mul_f32_e32 v51, v64, v54
	v_mul_f32_e32 v54, v65, v55
	v_mul_f32_e32 v55, 0xbfb8aa3b, v58
	v_mul_f32_e32 v51, v56, v51
	v_exp_f32_e32 v55, v55
	v_mul_f32_e32 v56, 0xbfb8aa3b, v59
	v_exp_f32_e32 v56, v56
	v_mul_f32_e32 v54, v57, v54
	v_add_f32_e32 v55, 1.0, v55
	v_rcp_f32_e32 v55, v55
	v_add_f32_e32 v56, 1.0, v56
	v_rcp_f32_e32 v56, v56
	v_cvt_pk_bf16_f32 v51, v51, v54
	v_mul_f32_e32 v54, v58, v55
	v_mul_f32_e32 v55, 0xbfb8aa3b, v60
	v_mul_f32_e32 v52, v52, v54
	v_mul_f32_e32 v54, v59, v56
	v_exp_f32_e32 v55, v55
	v_mul_f32_e32 v56, 0xbfb8aa3b, v61
	v_exp_f32_e32 v56, v56
	v_mul_f32_e32 v53, v53, v54
	v_add_f32_e32 v54, 1.0, v55
	v_rcp_f32_e32 v54, v54
	v_add_f32_e32 v55, 1.0, v56
	v_rcp_f32_e32 v55, v55
	v_cvt_pk_bf16_f32 v52, v52, v53
	v_mul_f32_e32 v53, v60, v54
	v_mul_f32_e32 v53, v72, v53
	v_mul_f32_e32 v54, v61, v55
	v_mul_f32_e32 v54, v73, v54
	v_cvt_pk_bf16_f32 v53, v53, v54
	global_store_dwordx4 v[70:71], v[50:53], off
	s_nop 1
	v_add_u32_e32 v50, 0x90, v146
	v_ashrrev_i32_e32 v51, 31, v50
	s_cbranch_vccnz .LBB0_437
	v_readlane_b32 s28, v245, 16
	v_readlane_b32 s29, v245, 17
	s_nop 1
	v_lshl_add_u64 v[52:53], v[50:51], 2, s[28:29]
	v_mov_b32_e32 v66, v191
.LBB0_437:
	v_pk_mul_f32 v[46:47], v[46:47], v[66:67] op_sel_hi:[1,0]
	v_pk_mul_f32 v[52:53], v[36:37], v[66:67] op_sel_hi:[1,0]
	v_mul_f32_e32 v36, 0xbfb8aa3b, v46
	v_exp_f32_e32 v36, v36
	v_pk_mul_f32 v[54:55], v[34:35], v[66:67] op_sel_hi:[1,0]
	v_mul_f32_e32 v37, 0xbfb8aa3b, v47
	v_exp_f32_e32 v37, v37
	v_add_f32_e32 v34, 1.0, v36
	v_rcp_f32_e32 v35, v34
	v_pk_mul_f32 v[48:49], v[48:49], v[66:67] op_sel_hi:[1,0]
	v_pk_mul_f32 v[38:39], v[38:39], v[66:67] op_sel_hi:[1,0]
	v_add_f32_e32 v34, 1.0, v37
	v_mul_f32_e32 v35, v46, v35
	v_mul_f32_e32 v35, v38, v35
	v_mul_f32_e32 v37, 0xbfb8aa3b, v48
	v_mul_f32_e32 v38, 0xbfb8aa3b, v49
	v_exp_f32_e32 v37, v37
	v_exp_f32_e32 v38, v38
	v_rcp_f32_e32 v36, v34
	v_pk_mul_f32 v[42:43], v[42:43], v[66:67] op_sel_hi:[1,0]
	v_add_f32_e32 v37, 1.0, v37
	v_add_f32_e32 v38, 1.0, v38
	v_rcp_f32_e32 v37, v37
	v_rcp_f32_e32 v38, v38
	v_mul_f32_e32 v36, v47, v36
	v_mul_f32_e32 v36, v39, v36
	v_cvt_pk_bf16_f32 v36, v35, v36
	v_mul_f32_e32 v35, v48, v37
	v_mul_f32_e32 v37, v49, v38
	v_mul_f32_e32 v38, 0xbfb8aa3b, v42
	v_mul_f32_e32 v39, 0xbfb8aa3b, v43
	v_exp_f32_e32 v38, v38
	v_exp_f32_e32 v39, v39
	v_pk_mul_f32 v[40:41], v[40:41], v[66:67] op_sel_hi:[1,0]
	v_pk_mul_f32 v[44:45], v[44:45], v[66:67] op_sel_hi:[1,0]
	v_add_f32_e32 v38, 1.0, v38
	v_add_f32_e32 v39, 1.0, v39
	v_rcp_f32_e32 v38, v38
	v_rcp_f32_e32 v39, v39
	v_mul_f32_e32 v35, v40, v35
	v_mul_f32_e32 v37, v41, v37
	v_cvt_pk_bf16_f32 v37, v35, v37
	v_mul_f32_e32 v35, v42, v38
	v_mul_f32_e32 v38, v43, v39
	v_mul_f32_e32 v39, 0xbfb8aa3b, v44
	v_mul_f32_e32 v40, 0xbfb8aa3b, v45
	v_exp_f32_e32 v39, v39
	v_exp_f32_e32 v40, v40
	v_readlane_b32 s28, v245, 14
	v_lshlrev_b64 v[50:51], 7, v[50:51]
	v_add_f32_e32 v39, 1.0, v39
	v_add_f32_e32 v40, 1.0, v40
	v_rcp_f32_e32 v39, v39
	v_rcp_f32_e32 v40, v40
	v_readlane_b32 s29, v245, 15
	v_mul_f32_e32 v35, v54, v35
	v_mul_f32_e32 v38, v55, v38
	v_lshl_add_u64 v[50:51], s[28:29], 0, v[50:51]
	v_cvt_pk_bf16_f32 v38, v35, v38
	v_mul_f32_e32 v35, v44, v39
	v_mul_f32_e32 v39, v45, v40
	v_lshl_add_u64 v[50:51], v[148:149], 1, v[50:51]
	v_mul_f32_e32 v39, v53, v39
	v_mul_f32_e32 v35, v52, v35
	v_cvt_pk_bf16_f32 v39, v35, v39
	global_store_dwordx4 v[50:51], v[36:39], off
	v_mov_b32_e32 v34, 1.0
	s_and_b64 vcc, exec, s[8:9]
	v_add_u32_e32 v38, 0xa0, v146
	v_ashrrev_i32_e32 v39, 31, v38
	v_mov_b32_e32 v36, 1.0
	s_cbranch_vccnz .LBB0_439
	v_readlane_b32 s28, v245, 16
	v_readlane_b32 s29, v245, 17
	s_nop 1
	v_lshl_add_u64 v[36:37], v[38:39], 2, s[28:29]
	v_mov_b32_e32 v36, v192
.LBB0_439:
	v_pk_mul_f32 v[30:31], v[30:31], v[36:37] op_sel_hi:[1,0]
	v_pk_mul_f32 v[32:33], v[32:33], v[36:37] op_sel_hi:[1,0]
	v_pk_mul_f32 v[28:29], v[28:29], v[36:37] op_sel_hi:[1,0]
	v_pk_mul_f32 v[26:27], v[26:27], v[36:37] op_sel_hi:[1,0]
	v_pk_mul_f32 v[24:25], v[24:25], v[36:37] op_sel_hi:[1,0]
	v_pk_mul_f32 v[22:23], v[22:23], v[36:37] op_sel_hi:[1,0]
	v_mul_f32_e32 v35, 0xbfb8aa3b, v30
	v_mul_f32_e32 v37, 0xbfb8aa3b, v31
	v_exp_f32_e32 v35, v35
	v_exp_f32_e32 v37, v37
	v_readlane_b32 s28, v245, 14
	v_lshlrev_b64 v[38:39], 7, v[38:39]
	v_readlane_b32 s29, v245, 15
	v_pk_mul_f32 v[40:41], v[20:21], v[36:37] op_sel_hi:[1,0]
	v_add_f32_e32 v20, 1.0, v35
	v_rcp_f32_e32 v35, v20
	v_add_f32_e32 v20, 1.0, v37
	v_rcp_f32_e32 v37, v20
	v_lshl_add_u64 v[38:39], s[28:29], 0, v[38:39]
	v_lshl_add_u64 v[38:39], v[148:149], 1, v[38:39]
	s_and_b64 vcc, exec, s[8:9]
	v_pk_mul_f32 v[20:21], v[18:19], v[36:37] op_sel_hi:[1,0]
	v_mul_f32_e32 v18, v30, v35
	v_mul_f32_e32 v18, v22, v18
	v_mul_f32_e32 v22, 0xbfb8aa3b, v32
	v_mul_f32_e32 v30, 0xbfb8aa3b, v33
	v_exp_f32_e32 v22, v22
	v_exp_f32_e32 v30, v30
	v_mul_f32_e32 v19, v31, v37
	v_mul_f32_e32 v19, v23, v19
	v_add_f32_e32 v22, 1.0, v22
	v_add_f32_e32 v23, 1.0, v30
	v_rcp_f32_e32 v22, v22
	v_rcp_f32_e32 v23, v23
	v_cvt_pk_bf16_f32 v18, v18, v19
	v_mul_f32_e32 v19, v32, v22
	v_mul_f32_e32 v22, v33, v23
	v_mul_f32_e32 v23, 0xbfb8aa3b, v26
	v_mul_f32_e32 v19, v24, v19
	v_exp_f32_e32 v23, v23
	v_mul_f32_e32 v24, 0xbfb8aa3b, v27
	v_exp_f32_e32 v24, v24
	v_mul_f32_e32 v22, v25, v22
	v_add_f32_e32 v23, 1.0, v23
	v_rcp_f32_e32 v23, v23
	v_add_f32_e32 v24, 1.0, v24
	v_rcp_f32_e32 v24, v24
	v_cvt_pk_bf16_f32 v19, v19, v22
	v_mul_f32_e32 v22, v26, v23
	v_mul_f32_e32 v23, 0xbfb8aa3b, v28
	v_mul_f32_e32 v20, v20, v22
	v_mul_f32_e32 v22, v27, v24
	v_exp_f32_e32 v23, v23
	v_mul_f32_e32 v24, 0xbfb8aa3b, v29
	v_exp_f32_e32 v24, v24
	v_mul_f32_e32 v21, v21, v22
	v_add_f32_e32 v22, 1.0, v23
	v_rcp_f32_e32 v22, v22
	v_add_f32_e32 v23, 1.0, v24
	v_rcp_f32_e32 v23, v23
	v_cvt_pk_bf16_f32 v20, v20, v21
	v_mul_f32_e32 v21, v28, v22
	v_mul_f32_e32 v21, v40, v21
	v_mul_f32_e32 v22, v29, v23
	v_mul_f32_e32 v22, v41, v22
	v_cvt_pk_bf16_f32 v21, v21, v22
	global_store_dwordx4 v[38:39], v[18:21], off
	s_nop 1
	v_add_u32_e32 v18, 0xb0, v146
	v_ashrrev_i32_e32 v19, 31, v18
	s_cbranch_vccnz .LBB0_441
	v_readlane_b32 s8, v245, 16
	v_readlane_b32 s9, v245, 17
	s_nop 1
	v_lshl_add_u64 v[20:21], v[18:19], 2, s[8:9]
	v_mov_b32_e32 v34, v193
.LBB0_441:
	v_pk_mul_f32 v[14:15], v[14:15], v[34:35] op_sel_hi:[1,0]
	v_pk_mul_f32 v[16:17], v[16:17], v[34:35] op_sel_hi:[1,0]
	v_mul_f32_e32 v20, 0xbfb8aa3b, v14
	v_exp_f32_e32 v22, v20
	v_mul_f32_e32 v20, 0xbfb8aa3b, v15
	v_exp_f32_e32 v23, v20
	v_pk_mul_f32 v[20:21], v[4:5], v[34:35] op_sel_hi:[1,0]
	v_add_f32_e32 v4, 1.0, v22
	v_rcp_f32_e32 v22, v4
	v_add_f32_e32 v4, 1.0, v23
	v_pk_mul_f32 v[6:7], v[6:7], v[34:35] op_sel_hi:[1,0]
	v_rcp_f32_e32 v23, v4
	v_pk_mul_f32 v[4:5], v[2:3], v[34:35] op_sel_hi:[1,0]
	v_mul_f32_e32 v2, v14, v22
	v_mul_f32_e32 v2, v6, v2
	v_mul_f32_e32 v6, 0xbfb8aa3b, v16
	v_mul_f32_e32 v14, 0xbfb8aa3b, v17
	v_exp_f32_e32 v6, v6
	v_exp_f32_e32 v14, v14
	v_mul_f32_e32 v3, v15, v23
	v_mul_f32_e32 v3, v7, v3
	v_add_f32_e32 v6, 1.0, v6
	v_add_f32_e32 v7, 1.0, v14
	v_rcp_f32_e32 v6, v6
	v_rcp_f32_e32 v7, v7
	v_pk_mul_f32 v[10:11], v[10:11], v[34:35] op_sel_hi:[1,0]
	v_pk_mul_f32 v[8:9], v[8:9], v[34:35] op_sel_hi:[1,0]
	v_cvt_pk_bf16_f32 v2, v2, v3
	v_mul_f32_e32 v3, v16, v6
	v_mul_f32_e32 v6, v17, v7
	v_mul_f32_e32 v7, 0xbfb8aa3b, v10
	v_mul_f32_e32 v3, v8, v3
	v_exp_f32_e32 v7, v7
	v_mul_f32_e32 v8, 0xbfb8aa3b, v11
	v_exp_f32_e32 v8, v8
	v_pk_mul_f32 v[12:13], v[12:13], v[34:35] op_sel_hi:[1,0]
	v_add_f32_e32 v7, 1.0, v7
	v_rcp_f32_e32 v7, v7
	v_add_f32_e32 v8, 1.0, v8
	v_rcp_f32_e32 v8, v8
	v_mul_f32_e32 v6, v9, v6
	v_cvt_pk_bf16_f32 v3, v3, v6
	v_mul_f32_e32 v6, v10, v7
	v_mul_f32_e32 v7, 0xbfb8aa3b, v12
	v_mul_f32_e32 v4, v4, v6
	v_mul_f32_e32 v6, v11, v8
	v_exp_f32_e32 v7, v7
	v_mul_f32_e32 v8, 0xbfb8aa3b, v13
	v_exp_f32_e32 v8, v8
	v_mul_f32_e32 v5, v5, v6
	v_add_f32_e32 v6, 1.0, v7
	v_rcp_f32_e32 v6, v6
	v_add_f32_e32 v7, 1.0, v8
	v_rcp_f32_e32 v7, v7
	v_readlane_b32 s8, v245, 14
	v_lshlrev_b64 v[18:19], 7, v[18:19]
	v_readlane_b32 s9, v245, 15
	v_cvt_pk_bf16_f32 v4, v4, v5
	v_mul_f32_e32 v5, v12, v6
	v_mul_f32_e32 v5, v20, v5
	v_lshl_add_u64 v[18:19], s[8:9], 0, v[18:19]
	v_lshl_add_u64 v[18:19], v[148:149], 1, v[18:19]
	v_mul_f32_e32 v6, v13, v7
	s_andn2_b64 vcc, exec, s[6:7]
	s_mov_b64 s[6:7], -1
	v_mul_f32_e32 v6, v21, v6
	v_cvt_pk_bf16_f32 v5, v5, v6
	global_store_dwordx4 v[18:19], v[2:5], off
	s_cbranch_vccnz .LBB0_418
	s_andn2_b64 vcc, exec, s[2:3]
	s_cbranch_vccnz .LBB0_417
	s_barrier
	s_branch .LBB0_417
